# row exchanges read partner partials with sc1 loads and skip the L1 invalidate in XCD-local mode (fallback keeps it)
# baseline (speedup 1.0000x reference)
.LBB0_595:
	s_waitcnt lgkmcnt(0)
	s_cmp_eq_u32 s99, 1
	s_cbranch_scc1 .Lxni_595
	buffer_inv sc1

.LBB0_596:
	s_or_b64 exec, exec, s[34:35]
	v_lshlrev_b32_e32 v8, 2, v244
	s_waitcnt lgkmcnt(1)
	v_ashrrev_i32_e32 v9, 31, v8
	v_lshl_add_u64 v[116:117], v[8:9], 3, s[42:43]
	s_barrier
	v_lshl_add_u64 v[8:9], v[116:117], 0, v[18:19]
	global_load_dwordx4 v[134:137], v[8:9], off sc1
	global_load_dwordx4 v[138:141], v[8:9], off offset:16 sc1
	s_ashr_i32 s83, s82, 31
	s_or_b32 s34, s26, s91
	s_lshl_b64 s[0:1], s[82:83], 2
	v_readlane_b32 s35, v254, 59
	s_add_u32 s0, s35, s0
	v_readlane_b32 s35, v254, 60
	s_addc_u32 s1, s35, s1
	v_lshl_add_u64 v[2:3], v[116:117], 0, v[2:3]
	v_lshl_add_u64 v[4:5], v[116:117], 0, v[4:5]
	global_load_dword v133, v169, s[0:1]
	v_lshl_add_u64 v[124:125], v[116:117], 0, v[6:7]
	global_load_dwordx4 v[22:25], v[2:3], off offset:16 sc1
	global_load_dwordx4 v[18:21], v[2:3], off sc1
	global_load_dwordx4 v[14:17], v[4:5], off offset:16 sc1
	s_waitcnt lgkmcnt(0)
	global_load_dwordx4 v[10:13], v[4:5], off sc1
	global_load_dwordx4 v[6:9], v[124:125], off offset:16 sc1
	s_nop 0
	global_load_dwordx4 v[2:5], v[124:125], off sc1
	s_waitcnt vmcnt(8)
	v_mov_b32_e32 v124, v134
	s_waitcnt vmcnt(7)
	v_mov_b32_e32 v125, v138
	v_mov_b32_e32 v130, v136
	v_mov_b32_e32 v131, v140
	v_pk_add_f32 v[124:125], v[124:125], v[130:131]
	v_max_f32_e32 v132, v141, v141
	v_add_f32_e32 v124, v124, v125
	ds_bpermute_b32 v125, v122, v124
	v_max_f32_e32 v134, v139, v139
	v_max_f32_e32 v130, v134, v132
	v_max3_f32 v130, v135, v137, v130
	ds_bpermute_b32 v131, v122, v130
	s_waitcnt lgkmcnt(1)
	v_add_f32_e32 v124, v124, v125
	ds_bpermute_b32 v125, v123, v124
	v_or_b32_e32 v132, s34, v244
	v_cmp_eq_u32_e32 vcc, 0, v132
	s_waitcnt lgkmcnt(1)
	v_max_f32_e32 v131, v131, v131
	v_max_f32_e32 v130, v130, v131
	s_waitcnt lgkmcnt(0)
	v_add_f32_e32 v124, v124, v125
	v_fmamk_f32 v124, v124, 0x3a800000, v240
	ds_bpermute_b32 v131, v123, v130
	v_mul_f32_e32 v125, 0x4b800000, v124
	v_cmp_gt_f32_e64 s[0:1], s96, v124
	s_nop 1
	v_cndmask_b32_e64 v124, v124, v125, s[0:1]
	v_rsq_f32_e32 v124, v124
	s_waitcnt lgkmcnt(0)
	v_max_f32_e32 v125, v131, v131
	v_max_f32_e32 v125, v130, v125
	v_mul_f32_e32 v130, 0x45800000, v124
	v_cndmask_b32_e64 v124, v124, v130, s[0:1]
	s_waitcnt vmcnt(6)
	v_fma_f32 v125, v125, v124, v133
	s_and_saveexec_b64 s[0:1], vcc
	s_cbranch_execz .LBB0_598
	v_mul_f32_e32 v132, 0x3c010204, v125
	v_lshl_add_u64 v[130:131], v[176:177], 2, s[6:7]
	global_store_dword v[130:131], v132, off

.LBB0_604:
	s_or_b64 exec, exec, s[0:1]
	v_lshl_add_u64 v[2:3], v[116:117], 0, v[92:93]
	global_load_dwordx4 v[134:137], v[2:3], off sc1
	global_load_dwordx4 v[138:141], v[2:3], off offset:16 sc1
	v_lshl_add_u64 v[2:3], v[116:117], 0, v[100:101]
	v_lshl_add_u64 v[4:5], v[116:117], 0, v[108:109]
	v_lshl_add_u64 v[82:83], v[116:117], 0, v[114:115]
	global_load_dwordx4 v[22:25], v[2:3], off offset:16 sc1
	global_load_dwordx4 v[18:21], v[2:3], off sc1
	global_load_dwordx4 v[14:17], v[4:5], off offset:16 sc1
	global_load_dwordx4 v[10:13], v[4:5], off sc1
	global_load_dwordx4 v[6:9], v[82:83], off offset:16 sc1
	s_nop 0
	global_load_dwordx4 v[2:5], v[82:83], off sc1
	s_waitcnt vmcnt(7)
	v_mov_b32_e32 v82, v134
	s_waitcnt vmcnt(6)
	v_mov_b32_e32 v83, v138
	v_mov_b32_e32 v92, v136
	v_mov_b32_e32 v93, v140
	v_pk_add_f32 v[82:83], v[82:83], v[92:93]
	v_max_f32_e32 v77, v141, v141
	v_add_f32_e32 v82, v82, v83
	ds_bpermute_b32 v83, v122, v82
	v_max_f32_e32 v100, v139, v139
	v_max_f32_e32 v77, v100, v77
	v_max3_f32 v77, v135, v137, v77
	ds_bpermute_b32 v92, v122, v77
	s_waitcnt lgkmcnt(1)
	v_add_f32_e32 v82, v82, v83
	ds_bpermute_b32 v83, v123, v82
	s_waitcnt lgkmcnt(1)
	v_max_f32_e32 v92, v92, v92
	v_max_f32_e32 v77, v77, v92
	s_waitcnt lgkmcnt(0)
	v_add_f32_e32 v82, v82, v83
	v_fmamk_f32 v82, v82, 0x3a800000, v240
	ds_bpermute_b32 v92, v123, v77
	v_mul_f32_e32 v83, 0x4b800000, v82
	v_cmp_gt_f32_e64 s[0:1], s96, v82
	s_nop 1
	v_cndmask_b32_e64 v82, v82, v83, s[0:1]
	v_rsq_f32_e32 v82, v82
	s_waitcnt lgkmcnt(0)
	v_max_f32_e32 v83, v92, v92
	v_max_f32_e32 v83, v77, v83
	v_mul_f32_e32 v77, 0x45800000, v82
	v_cndmask_b32_e64 v77, v82, v77, s[0:1]
	v_fma_f32 v82, v83, v77, v133
	s_and_saveexec_b64 s[0:1], vcc
	s_cbranch_execz .LBB0_606
	v_mul_f32_e32 v83, 0x3c010204, v82
	v_lshl_add_u64 v[84:85], v[84:85], 2, s[6:7]
	global_store_dword v[84:85], v83, off

.LBB0_749:
	s_or_b64 exec, exec, s[6:7]
	v_lshlrev_b32_e32 v2, 2, v225
	s_waitcnt lgkmcnt(0)
	v_ashrrev_i32_e32 v3, 31, v2
	v_lshl_add_u64 v[2:3], v[2:3], 2, s[30:31]
	s_barrier
	v_lshl_add_u64 v[4:5], v[2:3], 0, v[196:197]
	global_load_dwordx4 v[8:11], v[4:5], off sc1
	v_lshl_add_u64 v[4:5], v[2:3], 0, v[176:177]
	global_load_dwordx4 v[12:15], v[4:5], off sc1
	v_lshl_add_u64 v[4:5], v[2:3], 0, v[168:169]
	global_load_dwordx4 v[154:157], v[4:5], off sc1
	v_lshl_add_u64 v[4:5], v[2:3], 0, v[160:161]
	global_load_dwordx4 v[158:161], v[4:5], off sc1
	v_lshl_add_u64 v[4:5], v[2:3], 0, v[152:153]
	global_load_dwordx4 v[162:165], v[4:5], off sc1
	v_lshl_add_u64 v[4:5], v[2:3], 0, v[148:149]
	global_load_dwordx4 v[166:169], v[4:5], off sc1
	v_lshl_add_u64 v[6:7], v[2:3], 0, v[150:151]
	v_lshl_add_u64 v[0:1], v[2:3], 0, v[0:1]
	global_load_dwordx4 v[170:173], v[6:7], off sc1
	global_load_dwordx4 v[174:177], v[0:1], off sc1
	s_add_i32 s64, s64, s83
	v_add_u32_e32 v4, s64, v223
	s_add_u32 s64, s71, s66
	v_ashrrev_i32_e32 v5, 31, v4
	v_readlane_b32 s48, v254, 0
	s_addc_u32 s65, s72, s67
	v_lshlrev_b64 v[2:3], 2, v[4:5]
	v_readlane_b32 s52, v254, 4
	v_readlane_b32 s53, v254, 5
	s_add_u32 s66, s73, s66
	v_add_u32_e32 v132, 0x80, v4
	v_lshl_add_u64 v[0:1], s[52:53], 0, v[2:3]
	v_lshl_add_u64 v[4:5], s[64:65], 0, v[2:3]
	s_addc_u32 s67, s74, s67
	global_load_dwordx4 v[178:181], v[0:1], off offset:16
	global_load_dwordx4 v[192:195], v[0:1], off
	global_load_dwordx4 v[196:199], v[4:5], off offset:16
	global_load_dwordx4 v[200:203], v[4:5], off
	v_lshl_add_u64 v[4:5], s[66:67], 0, v[2:3]
	global_load_dwordx4 v[0:3], v[4:5], off offset:16
	s_nop 0
	global_load_dwordx4 v[4:7], v[4:5], off
	v_mov_b64_e32 v[182:183], s[58:59]
	v_readlane_b32 s54, v254, 6
	v_readlane_b32 s55, v254, 7
	v_ashrrev_i32_e32 v133, 31, v132
	v_readlane_b32 s49, v254, 1
	v_readlane_b32 s50, v254, 2
	v_readlane_b32 s51, v254, 3
	s_waitcnt vmcnt(13)
	v_mov_b32_e32 v134, v9
	v_mov_b32_e32 v135, v10
	v_mov_b32_e32 v9, v11
	s_waitcnt vmcnt(12)
	v_mov_b32_e32 v10, v13
	v_mov_b32_e32 v11, v14
	v_mov_b32_e32 v13, v15
	s_waitcnt vmcnt(11)
	v_mov_b32_e32 v14, v155
	v_mov_b32_e32 v15, v156
	v_mov_b32_e32 v155, v157
	s_waitcnt vmcnt(10)
	v_mov_b32_e32 v148, v159
	v_mov_b32_e32 v149, v160
	v_mov_b32_e32 v159, v161
	s_waitcnt vmcnt(9)
	v_mov_b32_e32 v150, v163
	v_mov_b32_e32 v151, v164
	v_mov_b32_e32 v163, v165
	v_pk_add_f32 v[8:9], v[134:135], v[8:9]
	v_pk_add_f32 v[10:11], v[10:11], v[12:13]
	v_pk_add_f32 v[12:13], v[14:15], v[154:155]
	v_pk_add_f32 v[14:15], v[148:149], v[158:159]
	v_pk_add_f32 v[134:135], v[150:151], v[162:163]
	v_mov_b32_e32 v150, v10
	v_mov_b32_e32 v151, v8
	v_mov_b32_e32 v8, v11
	v_mov_b32_e32 v10, v14
	v_mov_b32_e32 v11, v12
	v_mov_b32_e32 v12, v15
	v_pk_add_f32 v[8:9], v[150:151], v[8:9]
	v_pk_add_f32 v[10:11], v[10:11], v[12:13]
	ds_bpermute_b32 v13, v222, v9
	ds_bpermute_b32 v12, v222, v8
	ds_bpermute_b32 v15, v222, v11
	ds_bpermute_b32 v14, v222, v10
	s_waitcnt vmcnt(8)
	v_mov_b32_e32 v152, v167
	v_mov_b32_e32 v153, v168
	s_waitcnt lgkmcnt(2)
	v_pk_add_f32 v[8:9], v[8:9], v[12:13]
	ds_bpermute_b32 v13, v224, v9
	ds_bpermute_b32 v12, v224, v8
	s_waitcnt lgkmcnt(2)
	v_pk_add_f32 v[10:11], v[10:11], v[14:15]
	ds_bpermute_b32 v15, v224, v11
	ds_bpermute_b32 v14, v224, v10
	v_mov_b32_e32 v167, v169
	s_waitcnt lgkmcnt(2)
	v_pk_add_f32 v[8:9], v[8:9], v[12:13]
	v_pk_add_f32 v[148:149], v[152:153], v[166:167]
	v_pk_fma_f32 v[8:9], v[8:9], s[56:57], v[182:183] op_sel_hi:[1,0,0]
	v_mov_b32_e32 v150, v148
	v_mul_f32_e32 v12, 0x4b800000, v9
	v_cmp_gt_f32_e32 vcc, s91, v9
	v_mov_b32_e32 v151, v134
	v_mov_b32_e32 v134, v149
	v_cndmask_b32_e32 v9, v9, v12, vcc
	s_waitcnt lgkmcnt(0)
	v_pk_add_f32 v[10:11], v[10:11], v[14:15]
	v_rsq_f32_e32 v9, v9
	v_pk_add_f32 v[134:135], v[150:151], v[134:135]
	v_pk_fma_f32 v[10:11], v[10:11], s[56:57], v[182:183] op_sel_hi:[1,0,0]
	v_mul_f32_e32 v13, 0x4b800000, v8
	v_cmp_gt_f32_e64 s[0:1], s91, v8
	ds_bpermute_b32 v149, v222, v135
	ds_bpermute_b32 v148, v222, v134
	v_mul_f32_e32 v14, 0x4b800000, v11
	v_cndmask_b32_e64 v8, v8, v13, s[0:1]
	v_cmp_gt_f32_e64 s[6:7], s91, v11
	v_rsq_f32_e32 v12, v8
	s_waitcnt vmcnt(3)
	v_pk_add_f32 v[158:159], v[198:199], 1.0 op_sel_hi:[1,0]
	v_cndmask_b32_e64 v8, v11, v14, s[6:7]
	v_rsq_f32_e32 v13, v8
	v_mul_f32_e32 v8, 0x45800000, v9
	v_cndmask_b32_e32 v152, v9, v8, vcc
	v_mul_f32_e32 v8, 0x4b800000, v10
	v_cmp_gt_f32_e32 vcc, s91, v10
	v_mul_f32_e32 v14, 0x45800000, v12
	v_cndmask_b32_e64 v150, v12, v14, s[0:1]
	v_cndmask_b32_e32 v8, v10, v8, vcc
	v_rsq_f32_e32 v151, v8
	s_waitcnt lgkmcnt(0)
	v_pk_add_f32 v[8:9], v[134:135], v[148:149]
	ds_bpermute_b32 v11, v224, v9
	ds_bpermute_b32 v10, v224, v8
	v_mul_f32_e32 v12, 0x45800000, v13
	v_cndmask_b32_e64 v134, v13, v12, s[6:7]
	v_mov_b32_e32 v12, v175
	v_mov_b32_e32 v13, v176
	s_waitcnt lgkmcnt(0)
	v_pk_add_f32 v[8:9], v[8:9], v[10:11]
	v_mov_b32_e32 v11, v172
	v_pk_fma_f32 v[8:9], v[8:9], s[56:57], v[182:183] op_sel_hi:[1,0,0]
	v_mov_b32_e32 v175, v177
	v_mul_f32_e32 v10, 0x4b800000, v9
	v_cmp_gt_f32_e64 s[0:1], s91, v9
	v_pk_add_f32 v[12:13], v[12:13], v[174:175]
	v_cmp_gt_f32_e64 s[6:7], s91, v8
	v_cndmask_b32_e64 v9, v9, v10, s[0:1]
	v_mov_b32_e32 v10, v171
	v_mov_b32_e32 v171, v173
	v_pk_add_f32 v[10:11], v[10:11], v[170:171]
	v_mov_b32_e32 v14, v12
	v_mov_b32_e32 v15, v10
	v_mov_b32_e32 v10, v13
	v_pk_add_f32 v[10:11], v[14:15], v[10:11]
	ds_bpermute_b32 v13, v222, v11
	ds_bpermute_b32 v12, v222, v10
	v_rsq_f32_e32 v149, v9
	v_mul_f32_e32 v9, 0x4b800000, v8
	v_cndmask_b32_e64 v8, v8, v9, s[6:7]
	v_rsq_f32_e32 v15, v8
	s_waitcnt lgkmcnt(0)
	v_pk_add_f32 v[8:9], v[10:11], v[12:13]
	ds_bpermute_b32 v11, v224, v9
	ds_bpermute_b32 v10, v224, v8
	v_mul_f32_e32 v135, 0x45800000, v151
	v_cndmask_b32_e32 v148, v151, v135, vcc
	v_mul_f32_e32 v12, 0x45800000, v149
	v_pk_add_f32 v[160:161], v[196:197], 1.0 op_sel_hi:[1,0]
	s_waitcnt lgkmcnt(0)
	v_pk_add_f32 v[8:9], v[8:9], v[10:11]
	v_cndmask_b32_e64 v14, v149, v12, s[0:1]
	v_pk_fma_f32 v[8:9], v[8:9], s[56:57], v[182:183] op_sel_hi:[1,0,0]
	s_waitcnt vmcnt(2)
	v_pk_add_f32 v[156:157], v[200:201], 1.0 op_sel_hi:[1,0]
	v_mul_f32_e32 v10, 0x4b800000, v9
	v_cmp_gt_f32_e32 vcc, s91, v9
	v_cmp_gt_f32_e64 s[0:1], s91, v8
	v_pk_mul_f32 v[158:159], v[180:181], v[158:159]
	v_cndmask_b32_e32 v9, v9, v10, vcc
	v_rsq_f32_e32 v9, v9
	v_mul_f32_e32 v10, 0x4b800000, v8
	v_pk_mul_f32 v[160:161], v[178:179], v[160:161]
	v_pk_mul_f32 v[120:121], v[120:121], v[152:153] op_sel_hi:[1,0]
	v_pk_mul_f32 v[122:123], v[122:123], v[152:153] op_sel_hi:[1,0]
	v_cndmask_b32_e64 v8, v8, v10, s[0:1]
	v_mul_f32_e32 v10, 0x45800000, v9
	v_pk_mul_f32 v[156:157], v[192:193], v[156:157]
	v_lshl_add_u64 v[162:163], s[54:55], 0, v[240:241]
	s_waitcnt vmcnt(1)
	v_pk_fma_f32 v[122:123], v[122:123], v[158:159], v[2:3]
	v_pk_fma_f32 v[120:121], v[120:121], v[160:161], v[0:1]
	v_pk_mul_f32 v[108:109], v[108:109], v[150:151] op_sel_hi:[1,0]
	v_cndmask_b32_e32 v10, v9, v10, vcc
	global_store_dwordx4 v240, v[120:123], s[54:55] offset:16
	v_pk_mul_f32 v[104:105], v[104:105], v[150:151] op_sel_hi:[1,0]
	v_pk_mul_f32 v[106:107], v[106:107], v[150:151] op_sel_hi:[1,0]
	s_waitcnt vmcnt(1)
	v_pk_fma_f32 v[120:121], v[108:109], v[156:157], v[4:5]
	v_add_co_u32_e32 v108, vcc, s68, v162
	v_pk_fma_f32 v[106:107], v[106:107], v[158:159], v[2:3]
	s_nop 0
	v_addc_co_u32_e32 v109, vcc, 0, v163, vcc
	v_pk_fma_f32 v[104:105], v[104:105], v[160:161], v[0:1]
	v_pk_mul_f32 v[92:93], v[92:93], v[134:135] op_sel_hi:[1,0]
	global_store_dwordx4 v[108:109], v[104:107], off offset:16
	v_pk_mul_f32 v[88:89], v[88:89], v[134:135] op_sel_hi:[1,0]
	v_pk_mul_f32 v[90:91], v[90:91], v[134:135] op_sel_hi:[1,0]
	v_pk_fma_f32 v[104:105], v[92:93], v[156:157], v[4:5]
	v_add_co_u32_e32 v92, vcc, s95, v162
	v_pk_fma_f32 v[90:91], v[90:91], v[158:159], v[2:3]
	s_nop 0
	v_addc_co_u32_e32 v93, vcc, 0, v163, vcc
	v_pk_fma_f32 v[88:89], v[88:89], v[160:161], v[0:1]
	v_pk_mul_f32 v[76:77], v[76:77], v[148:149] op_sel_hi:[1,0]
	global_store_dwordx4 v[92:93], v[88:91], off offset:16
	v_pk_mul_f32 v[72:73], v[72:73], v[148:149] op_sel_hi:[1,0]
	v_pk_mul_f32 v[74:75], v[74:75], v[148:149] op_sel_hi:[1,0]
	v_pk_fma_f32 v[88:89], v[76:77], v[156:157], v[4:5]
	v_add_co_u32_e32 v76, vcc, s59, v162
	v_pk_fma_f32 v[74:75], v[74:75], v[158:159], v[2:3]
	s_nop 0
	v_addc_co_u32_e32 v77, vcc, 0, v163, vcc
	v_pk_fma_f32 v[72:73], v[72:73], v[160:161], v[0:1]
	v_mul_f32_e32 v12, 0x45800000, v15
	global_store_dwordx4 v[76:77], v[72:75], off offset:16
	v_cndmask_b32_e64 v12, v15, v12, s[6:7]
	v_rsq_f32_e32 v8, v8
	v_add_co_u32_e32 v72, vcc, s88, v162
	v_pk_add_f32 v[154:155], v[202:203], 1.0 op_sel_hi:[1,0]
	s_nop 0
	v_addc_co_u32_e32 v73, vcc, 0, v163, vcc
	v_add_co_u32_e32 v74, vcc, s89, v162
	v_pk_mul_f32 v[40:41], v[40:41], v[12:13] op_sel_hi:[1,0]
	v_pk_mul_f32 v[42:43], v[42:43], v[12:13] op_sel_hi:[1,0]
	v_pk_mul_f32 v[154:155], v[194:195], v[154:155]
	v_pk_mul_f32 v[78:79], v[78:79], v[148:149] op_sel_hi:[1,0]
	v_addc_co_u32_e32 v75, vcc, 0, v163, vcc
	v_pk_fma_f32 v[42:43], v[158:159], v[42:43], v[2:3]
	v_pk_fma_f32 v[40:41], v[160:161], v[40:41], v[0:1]
	v_pk_fma_f32 v[90:91], v[78:79], v[154:155], v[6:7]
	global_store_dwordx4 v[74:75], v[40:43], off offset:16
	v_add_co_u32_e32 v78, vcc, s90, v162
	s_nop 0
	v_pk_mul_f32 v[40:41], v[146:147], v[10:11] op_sel_hi:[1,0]
	v_pk_mul_f32 v[42:43], v[144:145], v[10:11] op_sel_hi:[1,0]
	v_pk_fma_f32 v[40:41], v[156:157], v[40:41], v[4:5]
	v_pk_fma_f32 v[42:43], v[154:155], v[42:43], v[6:7]
	v_addc_co_u32_e32 v79, vcc, 0, v163, vcc
	v_mul_f32_e32 v9, 0x45800000, v8
	global_store_dwordx4 v[78:79], v[40:43], off
	v_cndmask_b32_e64 v8, v8, v9, s[0:1]
	s_mov_b32 s0, 0xb0000
	v_pk_mul_f32 v[40:41], v[138:139], v[10:11] op_sel_hi:[1,0]
	v_pk_mul_f32 v[42:43], v[136:137], v[10:11] op_sel_hi:[1,0]
	v_pk_fma_f32 v[40:41], v[160:161], v[40:41], v[0:1]
	v_pk_fma_f32 v[42:43], v[158:159], v[42:43], v[2:3]
	v_pk_mul_f32 v[124:125], v[124:125], v[152:153] op_sel_hi:[1,0]
	v_pk_mul_f32 v[126:127], v[126:127], v[152:153] op_sel_hi:[1,0]
	v_pk_mul_f32 v[110:111], v[110:111], v[150:151] op_sel_hi:[1,0]
	v_pk_mul_f32 v[94:95], v[94:95], v[134:135] op_sel_hi:[1,0]
	global_store_dwordx4 v[76:77], v[88:91], off
	v_pk_mul_f32 v[60:61], v[60:61], v[14:15] op_sel_hi:[1,0]
	v_pk_mul_f32 v[62:63], v[62:63], v[14:15] op_sel_hi:[1,0]
	v_pk_mul_f32 v[44:45], v[44:45], v[12:13] op_sel_hi:[1,0]
	v_pk_mul_f32 v[46:47], v[46:47], v[12:13] op_sel_hi:[1,0]
	global_store_dwordx4 v[78:79], v[40:43], off offset:16
	v_add_co_u32_e32 v88, vcc, s0, v162
	s_nop 0
	v_pk_mul_f32 v[40:41], v[142:143], v[8:9] op_sel_hi:[1,0]
	v_pk_mul_f32 v[42:43], v[130:131], v[8:9] op_sel_hi:[1,0]
	v_pk_fma_f32 v[126:127], v[126:127], v[154:155], v[6:7]
	v_pk_fma_f32 v[124:125], v[124:125], v[156:157], v[4:5]
	v_pk_fma_f32 v[122:123], v[110:111], v[154:155], v[6:7]
	v_pk_fma_f32 v[106:107], v[94:95], v[154:155], v[6:7]
	v_pk_fma_f32 v[62:63], v[154:155], v[62:63], v[6:7]
	v_pk_fma_f32 v[60:61], v[156:157], v[60:61], v[4:5]
	v_pk_mul_f32 v[56:57], v[56:57], v[14:15] op_sel_hi:[1,0]
	v_pk_mul_f32 v[58:59], v[58:59], v[14:15] op_sel_hi:[1,0]
	v_pk_fma_f32 v[46:47], v[154:155], v[46:47], v[6:7]
	v_pk_fma_f32 v[44:45], v[156:157], v[44:45], v[4:5]
	v_pk_fma_f32 v[6:7], v[154:155], v[42:43], v[6:7]
	v_pk_fma_f32 v[4:5], v[156:157], v[40:41], v[4:5]
	v_addc_co_u32_e32 v89, vcc, 0, v163, vcc
	v_pk_fma_f32 v[58:59], v[58:59], v[158:159], v[2:3]
	v_pk_fma_f32 v[56:57], v[56:57], v[160:161], v[0:1]
	global_store_dwordx4 v[88:89], v[4:7], off
	global_store_dwordx4 v[72:73], v[56:59], off offset:16
	global_store_dwordx4 v240, v[124:127], s[54:55]
	v_pk_mul_f32 v[4:5], v[140:141], v[8:9] op_sel_hi:[1,0]
	v_pk_mul_f32 v[6:7], v[128:129], v[8:9] op_sel_hi:[1,0]
	v_pk_fma_f32 v[0:1], v[160:161], v[4:5], v[0:1]
	v_pk_fma_f32 v[2:3], v[158:159], v[6:7], v[2:3]
	v_lshlrev_b64 v[56:57], 2, v[132:133]
	global_store_dwordx4 v[108:109], v[120:123], off
	global_store_dwordx4 v[92:93], v[104:107], off
	global_store_dwordx4 v[72:73], v[60:63], off
	global_store_dwordx4 v[74:75], v[44:47], off
	global_store_dwordx4 v[88:89], v[0:3], off offset:16
	v_lshl_add_u64 v[40:41], s[64:65], 0, v[56:57]
	global_load_dwordx4 v[0:3], v[40:41], off
	v_lshl_add_u64 v[44:45], s[52:53], 0, v[56:57]
	global_load_dwordx4 v[4:7], v[44:45], off
	s_nop 0
	global_load_dwordx4 v[40:43], v[40:41], off offset:16
	s_nop 0
	global_load_dwordx4 v[44:47], v[44:45], off offset:16
	v_lshl_add_u64 v[60:61], s[66:67], 0, v[56:57]
	global_load_dwordx4 v[56:59], v[60:61], off
	s_nop 0
	global_load_dwordx4 v[60:63], v[60:61], off offset:16
	s_and_b64 vcc, exec, s[4:5]
	s_mov_b64 s[0:1], -1
	s_waitcnt vmcnt(5)
	v_pk_add_f32 v[2:3], v[2:3], 1.0 op_sel_hi:[1,0]
	v_pk_add_f32 v[0:1], v[0:1], 1.0 op_sel_hi:[1,0]
	s_waitcnt vmcnt(4)
	v_pk_mul_f32 v[6:7], v[6:7], v[2:3]
	v_pk_mul_f32 v[4:5], v[4:5], v[0:1]
	s_waitcnt vmcnt(3)
	v_pk_add_f32 v[0:1], v[42:43], 1.0 op_sel_hi:[1,0]
	v_pk_add_f32 v[2:3], v[40:41], 1.0 op_sel_hi:[1,0]
	s_waitcnt vmcnt(2)
	v_pk_mul_f32 v[40:41], v[46:47], v[0:1]
	v_pk_mul_f32 v[42:43], v[44:45], v[2:3]
	v_pk_mul_f32 v[2:3], v[118:119], v[152:153] op_sel_hi:[1,0]
	v_pk_mul_f32 v[0:1], v[116:117], v[152:153] op_sel_hi:[1,0]
	s_waitcnt vmcnt(1)
	v_pk_fma_f32 v[2:3], v[2:3], v[6:7], v[58:59]
	v_pk_fma_f32 v[0:1], v[0:1], v[4:5], v[56:57]
	global_store_dwordx4 v240, v[0:3], s[54:55] offset:512
	s_nop 1
	v_pk_mul_f32 v[2:3], v[114:115], v[152:153] op_sel_hi:[1,0]
	v_pk_mul_f32 v[0:1], v[112:113], v[152:153] op_sel_hi:[1,0]
	s_waitcnt vmcnt(1)
	v_pk_fma_f32 v[2:3], v[2:3], v[40:41], v[62:63]
	v_pk_fma_f32 v[0:1], v[0:1], v[42:43], v[60:61]
	global_store_dwordx4 v240, v[0:3], s[54:55] offset:528
	s_nop 1
	v_pk_mul_f32 v[2:3], v[102:103], v[150:151] op_sel_hi:[1,0]
	v_pk_mul_f32 v[0:1], v[100:101], v[150:151] op_sel_hi:[1,0]
	v_pk_fma_f32 v[2:3], v[2:3], v[6:7], v[58:59]
	v_pk_fma_f32 v[0:1], v[0:1], v[4:5], v[56:57]
	global_store_dwordx4 v[108:109], v[0:3], off offset:512
	s_nop 1
	v_pk_mul_f32 v[2:3], v[98:99], v[150:151] op_sel_hi:[1,0]
	v_pk_mul_f32 v[0:1], v[96:97], v[150:151] op_sel_hi:[1,0]
	v_pk_fma_f32 v[2:3], v[2:3], v[40:41], v[62:63]
	v_pk_fma_f32 v[0:1], v[0:1], v[42:43], v[60:61]
	global_store_dwordx4 v[108:109], v[0:3], off offset:528
	s_nop 1
	v_pk_mul_f32 v[2:3], v[86:87], v[134:135] op_sel_hi:[1,0]
	v_pk_mul_f32 v[0:1], v[84:85], v[134:135] op_sel_hi:[1,0]
	v_pk_fma_f32 v[2:3], v[2:3], v[6:7], v[58:59]
	v_pk_fma_f32 v[0:1], v[0:1], v[4:5], v[56:57]
	global_store_dwordx4 v[92:93], v[0:3], off offset:512
	s_nop 1
	v_pk_mul_f32 v[2:3], v[82:83], v[134:135] op_sel_hi:[1,0]
	v_pk_mul_f32 v[0:1], v[80:81], v[134:135] op_sel_hi:[1,0]
	v_pk_fma_f32 v[2:3], v[2:3], v[40:41], v[62:63]
	v_pk_fma_f32 v[0:1], v[0:1], v[42:43], v[60:61]
	global_store_dwordx4 v[92:93], v[0:3], off offset:528
	s_nop 1
	v_pk_mul_f32 v[2:3], v[70:71], v[148:149] op_sel_hi:[1,0]
	v_pk_mul_f32 v[0:1], v[68:69], v[148:149] op_sel_hi:[1,0]
	v_pk_fma_f32 v[2:3], v[2:3], v[6:7], v[58:59]
	v_pk_fma_f32 v[0:1], v[0:1], v[4:5], v[56:57]
	global_store_dwordx4 v[76:77], v[0:3], off offset:512
	s_nop 1
	v_pk_mul_f32 v[2:3], v[66:67], v[148:149] op_sel_hi:[1,0]
	v_pk_mul_f32 v[0:1], v[64:65], v[148:149] op_sel_hi:[1,0]
	v_pk_fma_f32 v[2:3], v[2:3], v[40:41], v[62:63]
	v_pk_fma_f32 v[0:1], v[0:1], v[42:43], v[60:61]
	global_store_dwordx4 v[76:77], v[0:3], off offset:528
	s_nop 1
	v_pk_mul_f32 v[2:3], v[54:55], v[14:15] op_sel_hi:[1,0]
	v_pk_mul_f32 v[0:1], v[52:53], v[14:15] op_sel_hi:[1,0]
	v_pk_fma_f32 v[2:3], v[2:3], v[6:7], v[58:59]
	v_pk_fma_f32 v[0:1], v[0:1], v[4:5], v[56:57]
	global_store_dwordx4 v[72:73], v[0:3], off offset:512
	s_nop 1
	v_pk_mul_f32 v[2:3], v[50:51], v[14:15] op_sel_hi:[1,0]
	v_pk_mul_f32 v[0:1], v[48:49], v[14:15] op_sel_hi:[1,0]
	v_pk_fma_f32 v[2:3], v[2:3], v[40:41], v[62:63]
	v_pk_fma_f32 v[0:1], v[0:1], v[42:43], v[60:61]
	global_store_dwordx4 v[72:73], v[0:3], off offset:528
	s_nop 1
	v_pk_mul_f32 v[2:3], v[38:39], v[12:13] op_sel_hi:[1,0]
	v_pk_mul_f32 v[0:1], v[36:37], v[12:13] op_sel_hi:[1,0]
	v_pk_fma_f32 v[2:3], v[2:3], v[6:7], v[58:59]
	v_pk_fma_f32 v[0:1], v[0:1], v[4:5], v[56:57]
	global_store_dwordx4 v[74:75], v[0:3], off offset:512
	s_nop 1
	v_pk_mul_f32 v[2:3], v[34:35], v[12:13] op_sel_hi:[1,0]
	v_pk_mul_f32 v[0:1], v[32:33], v[12:13] op_sel_hi:[1,0]
	v_pk_fma_f32 v[2:3], v[2:3], v[40:41], v[62:63]
	v_pk_fma_f32 v[0:1], v[0:1], v[42:43], v[60:61]
	global_store_dwordx4 v[74:75], v[0:3], off offset:528
	s_nop 1
	v_pk_mul_f32 v[2:3], v[22:23], v[10:11] op_sel_hi:[1,0]
	v_pk_mul_f32 v[0:1], v[20:21], v[10:11] op_sel_hi:[1,0]
	v_pk_fma_f32 v[2:3], v[2:3], v[6:7], v[58:59]
	v_pk_fma_f32 v[0:1], v[0:1], v[4:5], v[56:57]
	global_store_dwordx4 v[78:79], v[0:3], off offset:512
	s_nop 1
	v_pk_mul_f32 v[2:3], v[18:19], v[10:11] op_sel_hi:[1,0]
	v_pk_mul_f32 v[0:1], v[16:17], v[10:11] op_sel_hi:[1,0]
	v_pk_fma_f32 v[2:3], v[2:3], v[40:41], v[62:63]
	v_pk_fma_f32 v[0:1], v[0:1], v[42:43], v[60:61]
	global_store_dwordx4 v[78:79], v[0:3], off offset:528
	s_nop 1
	v_pk_mul_f32 v[2:3], v[26:27], v[8:9] op_sel_hi:[1,0]
	v_pk_mul_f32 v[0:1], v[30:31], v[8:9] op_sel_hi:[1,0]
	v_pk_fma_f32 v[2:3], v[2:3], v[6:7], v[58:59]
	v_pk_fma_f32 v[0:1], v[0:1], v[4:5], v[56:57]
	global_store_dwordx4 v[88:89], v[0:3], off offset:512
	s_nop 1
	v_pk_mul_f32 v[2:3], v[24:25], v[8:9] op_sel_hi:[1,0]
	v_pk_mul_f32 v[0:1], v[28:29], v[8:9] op_sel_hi:[1,0]
	v_pk_fma_f32 v[2:3], v[2:3], v[40:41], v[62:63]
	v_pk_fma_f32 v[0:1], v[0:1], v[42:43], v[60:61]
	global_store_dwordx4 v[88:89], v[0:3], off offset:528
	s_cbranch_vccnz .LBB0_709
	v_readlane_b32 s0, v254, 41
	v_readlane_b32 s1, v254, 42
	s_andn2_b64 vcc, exec, s[0:1]
	s_cbranch_vccnz .LBB0_708
	s_barrier
	s_branch .LBB0_708
